# fused branch-merge GEMM seam hook: gate-load waits re-derived per first consumer (counted) instead of vmcnt(0)
# speedup vs baseline: 1.0142x; 1.0005x over previous
;     static __device__ __forceinline__ void unpack(const u32x4 g4, f32x4& g0, f32x4& g1) { g0 = (f32x4){bflo(g4.x), bfhi(g4.x), bflo(g4.y), bfhi(g4.y)}; g1 = (f32x4){bflo(g4.z), bfhi(g4.z), bflo(g4.w), bfhi(g4.w)}; }
;     __device__ __forceinline__ void mid(f32x4 (&acc)[2][2][4][2], const Unit& u, int wr, int wc, int fr, int fq, bool second) const {
;     ...
;         const int on = second ? 2048 : 0, od = second ? 4096 : 2048;
;         const float nfloor = second ? 1e-20f : 0.f;
;         u32x4 gn[2][2], gd[2][2];
; #pragma unroll
;         for (int bj = 0; bj < 2; ++bj) { gn[0][bj] = *(const u32x4*)(GT + r0 * ldg + on + col0 + bj * HALF); gd[0][bj] = *(const u32x4*)(GT + r0 * ldg + od + col0 + bj * HALF); }
; #pragma unroll
;         for (int gi = 0; gi < 8; ++gi) {
;             const int ai = gi >> 2, m = gi & 3;
;             if (gi < 7) { const size_t row2 = r0 + ((gi + 1) >> 2) * HALF + ((gi + 1) & 3) * 16;
; #pragma unroll
;                 for (int bj = 0; bj < 2; ++bj) { gn[(gi + 1) & 1][bj] = *(const u32x4*)(GT + row2 * ldg + on + col0 + bj * HALF); gd[(gi + 1) & 1][bj] = *(const u32x4*)(GT + row2 * ldg + od + col0 + bj * HALF); } }
;             asm volatile("" ::: "memory");
; #pragma unroll
;             for (int bj = 0; bj < 2; ++bj) {
;                 f32x4 n0, n1, d0, d1; unpack(gn[gi & 1][bj], n0, n1); unpack(gd[gi & 1][bj], d0, d1);
; #pragma unroll
;                 for (int j = 0; j < 4; ++j) {
;                     acc[ai][bj][m][0][j] *= fmaxf(n0[j], nfloor) * __builtin_amdgcn_rcpf(fmaxf(d0[j], 1e-20f));
;                     acc[ai][bj][m][1][j] *= fmaxf(n1[j], nfloor) * __builtin_amdgcn_rcpf(fmaxf(d1[j], 1e-20f)); }
.LBB0_992:
	s_andn2_b64 vcc, exec, s[28:29]
	s_cbranch_vccnz .LBB0_994
	s_cmp_eq_u32 s62, 32
	s_cselect_b64 vcc, -1, 0
	s_and_b64 s[28:29], vcc, exec
	s_cselect_b32 s66, 0x1000, 0
	v_lshl_add_u64 v[4:5], v[188:189], 0, s[66:67]
	global_load_dwordx4 v[158:161], v[4:5], off
	s_mov_b32 s29, s67
	s_cselect_b32 s28, s71, 0x1000
	v_lshl_add_u64 v[134:135], v[188:189], 0, s[28:29]
	global_load_dwordx4 v[162:165], v[134:135], off
	global_load_dwordx4 v[154:157], v[4:5], off offset:256
	global_load_dwordx4 v[150:153], v[134:135], off offset:256
	v_lshl_add_u64 v[4:5], v[190:191], 0, s[66:67]
	v_lshl_add_u64 v[134:135], v[190:191], 0, s[28:29]
	global_load_dwordx4 v[146:149], v[4:5], off
	global_load_dwordx4 v[138:141], v[4:5], off offset:256
	global_load_dwordx4 v[142:145], v[134:135], off
	s_nop 0
	global_load_dwordx4 v[134:137], v[134:135], off offset:256
	v_mov_b32_e32 v3, 0x1e3ce508
	v_cndmask_b32_e32 v3, 0, v3, vcc
	s_waitcnt vmcnt(7)
	v_lshlrev_b32_e32 v4, 16, v158
	v_and_b32_e32 v5, 0xffff0000, v158
	v_lshlrev_b32_e32 v158, 16, v159
	v_lshlrev_b32_e32 v166, 16, v160
	v_lshlrev_b32_e32 v167, 16, v161
	s_waitcnt vmcnt(6)
	v_lshlrev_b32_e32 v168, 16, v162
	v_and_b32_e32 v162, 0xffff0000, v162
	v_lshlrev_b32_e32 v169, 16, v163
	v_and_b32_e32 v163, 0xffff0000, v163
	v_lshlrev_b32_e32 v170, 16, v164
	v_and_b32_e32 v164, 0xffff0000, v164
	v_lshlrev_b32_e32 v171, 16, v165
	v_and_b32_e32 v165, 0xffff0000, v165
	s_waitcnt vmcnt(5)
	v_lshlrev_b32_e32 v185, 16, v155
	v_and_b32_e32 v187, 0xffff0000, v155
	v_lshlrev_b32_e32 v192, 16, v156
	v_and_b32_e32 v193, 0xffff0000, v156
	v_lshlrev_b32_e32 v196, 16, v157
	v_and_b32_e32 v197, 0xffff0000, v157
	v_max_f32_e32 v155, v166, v166
	v_max_f32_e32 v156, v170, v170
	v_max_f32_e32 v157, v162, v162
	v_max_f32_e32 v162, v164, v164
	v_max_f32_e32 v158, v158, v158
	v_max_f32_e32 v164, v169, v169
	v_max_f32_e32 v166, v167, v167
	v_max_f32_e32 v167, v171, v171
	v_max_f32_e32 v163, v163, v163
	v_max_f32_e32 v165, v165, v165
	v_and_b32_e32 v159, 0xffff0000, v159
	v_and_b32_e32 v160, 0xffff0000, v160
	v_and_b32_e32 v161, 0xffff0000, v161
	v_lshlrev_b32_e32 v172, 16, v154
	v_and_b32_e32 v173, 0xffff0000, v154
	v_max_f32_e32 v154, v168, v168
	v_max_f32_e32 v169, 0x1e3ce508, v156
	v_max_f32_e32 v171, 0x1e3ce508, v162
	v_max_f32_e32 v156, v158, v3
	v_max_f32_e32 v164, 0x1e3ce508, v164
	v_max_f32_e32 v158, v166, v3
	v_max_f32_e32 v166, 0x1e3ce508, v167
	v_max_f32_e32 v167, 0x1e3ce508, v163
	v_max_f32_e32 v199, 0x1e3ce508, v165
	v_max_f32_e32 v160, v160, v160
	v_max_f32_e32 v159, v159, v159
	v_max_f32_e32 v161, v161, v161
	v_max_f32_e32 v168, 0x1e3ce508, v154
	v_max_f32_e32 v170, 0x1e3ce508, v157
	v_rcp_f32_e32 v162, v169
	v_rcp_f32_e32 v163, v171
	v_rcp_f32_e32 v164, v164
	v_rcp_f32_e32 v165, v167
	v_rcp_f32_e32 v166, v166
	v_rcp_f32_e32 v167, v199
	v_max_f32_e32 v154, v155, v3
	v_max_f32_e32 v155, v160, v3
	v_max_f32_e32 v157, v159, v3
	v_max_f32_e32 v159, v161, v3
	v_rcp_f32_e32 v160, v168
	v_rcp_f32_e32 v161, v170
	v_max_f32_e32 v4, v4, v4
	v_max_f32_e32 v5, v5, v5
	v_max_f32_e32 v4, v4, v3
	v_max_f32_e32 v5, v5, v3
	v_pk_mul_f32 v[156:157], v[156:157], v[164:165]
	v_pk_mul_f32 v[154:155], v[154:155], v[162:163]
	v_pk_mul_f32 v[158:159], v[158:159], v[166:167]
	s_waitcnt vmcnt(4)
	v_lshlrev_b32_e32 v198, 16, v150
	v_pk_mul_f32 v[4:5], v[4:5], v[160:161]
	v_pk_mul_f32 v[128:129], v[128:129], v[156:157]
	v_pk_mul_f32 v[132:133], v[132:133], v[158:159]
	v_pk_mul_f32 v[130:131], v[130:131], v[154:155]
	v_and_b32_e32 v155, 0xffff0000, v150
	v_lshlrev_b32_e32 v157, 16, v151
	v_and_b32_e32 v159, 0xffff0000, v151
	v_max_f32_e32 v151, v192, v192
	v_pk_mul_f32 v[126:127], v[126:127], v[4:5]
	v_lshlrev_b32_e32 v5, 16, v152
	v_and_b32_e32 v156, 0xffff0000, v152
	v_max_f32_e32 v150, v198, v198
	v_max_f32_e32 v152, v151, v3
	v_max_f32_e32 v151, v155, v155
	v_max_f32_e32 v150, 0x1e3ce508, v150
	v_max_f32_e32 v151, 0x1e3ce508, v151
	v_max_f32_e32 v157, v157, v157
	v_rcp_f32_e32 v150, v150
	v_max_f32_e32 v5, v5, v5
	v_rcp_f32_e32 v151, v151
	v_max_f32_e32 v157, 0x1e3ce508, v157
	v_lshlrev_b32_e32 v161, 16, v153
	v_max_f32_e32 v5, 0x1e3ce508, v5
	v_rcp_f32_e32 v158, v157
	v_max_f32_e32 v157, v196, v196
	v_max_f32_e32 v4, v172, v172
	v_rcp_f32_e32 v154, v5
	v_max_f32_e32 v5, v173, v173
	v_max_f32_e32 v160, v157, v3
	v_max_f32_e32 v157, v161, v161
	v_max_f32_e32 v4, v4, v3
	v_max_f32_e32 v5, v5, v3
	v_max_f32_e32 v157, 0x1e3ce508, v157
	v_and_b32_e32 v163, 0xffff0000, v153
	v_rcp_f32_e32 v162, v157
	v_max_f32_e32 v157, v159, v159
	v_pk_mul_f32 v[4:5], v[4:5], v[150:151]
	v_max_f32_e32 v155, v156, v156
	v_max_f32_e32 v157, 0x1e3ce508, v157
	v_pk_mul_f32 v[122:123], v[122:123], v[4:5]
	v_max_f32_e32 v4, v163, v163
	v_max_f32_e32 v155, 0x1e3ce508, v155
	v_rcp_f32_e32 v159, v157
	v_max_f32_e32 v4, 0x1e3ce508, v4
	v_rcp_f32_e32 v155, v155
	v_rcp_f32_e32 v163, v4
	v_max_f32_e32 v156, v185, v185
	v_max_f32_e32 v157, v187, v187
	v_max_f32_e32 v153, v193, v193
	v_max_f32_e32 v156, v156, v3
	v_max_f32_e32 v157, v157, v3
	v_max_f32_e32 v4, v197, v197
	v_max_f32_e32 v153, v153, v3
	v_pk_mul_f32 v[150:151], v[156:157], v[158:159]
	v_max_f32_e32 v161, v4, v3
	v_pk_mul_f32 v[124:125], v[124:125], v[150:151]
	v_pk_mul_f32 v[4:5], v[152:153], v[154:155]
	v_pk_mul_f32 v[150:151], v[160:161], v[162:163]
	v_pk_mul_f32 v[118:119], v[118:119], v[4:5]
	v_pk_mul_f32 v[120:121], v[120:121], v[150:151]
	v_lshl_add_u64 v[4:5], v[204:205], 0, s[66:67]
	v_lshl_add_u64 v[150:151], v[204:205], 0, s[28:29]
	global_load_dwordx4 v[166:169], v[4:5], off
	global_load_dwordx4 v[154:157], v[4:5], off offset:256
	global_load_dwordx4 v[158:161], v[150:151], off
	s_nop 0
	global_load_dwordx4 v[150:153], v[150:151], off offset:256
	s_waitcnt vmcnt(5)
;     static __device__ __forceinline__ void unpack(const u32x4 g4, f32x4& g0, f32x4& g1) { g0 = (f32x4){bflo(g4.x), bfhi(g4.x), bflo(g4.y), bfhi(g4.y)}; g1 = (f32x4){bflo(g4.z), bfhi(g4.z), bflo(g4.w), bfhi(g4.w)}; }
;     __device__ __forceinline__ void mid(f32x4 (&acc)[2][2][4][2], const Unit& u, int wr, int wc, int fr, int fq, bool second) const {
;     ...
;             if (gi < 7) { const size_t row2 = r0 + ((gi + 1) >> 2) * HALF + ((gi + 1) & 3) * 16;
; #pragma unroll
;                 for (int bj = 0; bj < 2; ++bj) { gn[(gi + 1) & 1][bj] = *(const u32x4*)(GT + row2 * ldg + on + col0 + bj * HALF); gd[(gi + 1) & 1][bj] = *(const u32x4*)(GT + row2 * ldg + od + col0 + bj * HALF); } }
;             asm volatile("" ::: "memory");
; #pragma unroll
;             for (int bj = 0; bj < 2; ++bj) {
;                 f32x4 n0, n1, d0, d1; unpack(gn[gi & 1][bj], n0, n1); unpack(gd[gi & 1][bj], d0, d1);
; #pragma unroll
;                 for (int j = 0; j < 4; ++j) {
;                     acc[ai][bj][m][0][j] *= fmaxf(n0[j], nfloor) * __builtin_amdgcn_rcpf(fmaxf(d0[j], 1e-20f));
;                     acc[ai][bj][m][1][j] *= fmaxf(n1[j], nfloor) * __builtin_amdgcn_rcpf(fmaxf(d1[j], 1e-20f)); }
	v_lshlrev_b32_e32 v164, 16, v143
	v_and_b32_e32 v171, 0xffff0000, v143
	v_lshlrev_b32_e32 v143, 16, v144
	v_max_f32_e32 v143, v143, v143
	v_lshlrev_b32_e32 v4, 16, v146
	v_and_b32_e32 v5, 0xffff0000, v146
	v_lshlrev_b32_e32 v162, 16, v147
	v_and_b32_e32 v165, 0xffff0000, v147
	v_lshlrev_b32_e32 v146, 16, v148
	v_and_b32_e32 v147, 0xffff0000, v148
	v_lshlrev_b32_e32 v163, 16, v149
	v_and_b32_e32 v172, 0xffff0000, v149
	v_lshlrev_b32_e32 v148, 16, v142
	v_and_b32_e32 v149, 0xffff0000, v142
	v_max_f32_e32 v143, 0x1e3ce508, v143
	v_and_b32_e32 v170, 0xffff0000, v144
	v_max_f32_e32 v142, v148, v148
	v_max_f32_e32 v144, v146, v146
	v_rcp_f32_e32 v146, v143
	v_max_f32_e32 v143, v149, v149
	v_max_f32_e32 v142, 0x1e3ce508, v142
	v_max_f32_e32 v143, 0x1e3ce508, v143
	v_max_f32_e32 v149, v164, v164
	v_rcp_f32_e32 v142, v142
	v_rcp_f32_e32 v143, v143
	v_max_f32_e32 v149, 0x1e3ce508, v149
	v_lshlrev_b32_e32 v173, 16, v145
	v_max_f32_e32 v148, v162, v162
	v_rcp_f32_e32 v162, v149
	v_max_f32_e32 v149, v163, v163
	v_max_f32_e32 v4, v4, v4
	v_max_f32_e32 v5, v5, v5
	v_max_f32_e32 v164, v149, v3
	v_max_f32_e32 v149, v173, v173
	v_max_f32_e32 v4, v4, v3
	v_max_f32_e32 v5, v5, v3
	v_max_f32_e32 v149, 0x1e3ce508, v149
	v_and_b32_e32 v185, 0xffff0000, v145
	v_max_f32_e32 v145, v147, v147
	v_max_f32_e32 v147, v170, v170
	v_rcp_f32_e32 v170, v149
	v_max_f32_e32 v149, v171, v171
	v_pk_mul_f32 v[4:5], v[4:5], v[142:143]
	v_max_f32_e32 v147, 0x1e3ce508, v147
	v_max_f32_e32 v149, 0x1e3ce508, v149
	v_pk_mul_f32 v[114:115], v[114:115], v[4:5]
	v_max_f32_e32 v4, v185, v185
	v_rcp_f32_e32 v147, v147
	v_rcp_f32_e32 v163, v149
	v_max_f32_e32 v4, 0x1e3ce508, v4
	v_rcp_f32_e32 v171, v4
	v_max_f32_e32 v149, v165, v165
	v_max_f32_e32 v144, v144, v3
	v_max_f32_e32 v145, v145, v3
	v_max_f32_e32 v148, v148, v3
	v_max_f32_e32 v149, v149, v3
	v_max_f32_e32 v4, v172, v172
	v_pk_mul_f32 v[142:143], v[148:149], v[162:163]
	v_max_f32_e32 v165, v4, v3
	v_pk_mul_f32 v[4:5], v[144:145], v[146:147]
	s_waitcnt vmcnt(4)
	v_lshlrev_b32_e32 v144, 16, v135
	v_and_b32_e32 v147, 0xffff0000, v135
	v_lshlrev_b32_e32 v135, 16, v136
	v_pk_mul_f32 v[116:117], v[116:117], v[142:143]
	v_pk_mul_f32 v[142:143], v[164:165], v[170:171]
	v_max_f32_e32 v135, v135, v135
	v_pk_mul_f32 v[112:113], v[112:113], v[142:143]
	v_pk_mul_f32 v[110:111], v[110:111], v[4:5]
	v_lshlrev_b32_e32 v4, 16, v138
	v_and_b32_e32 v5, 0xffff0000, v138
	v_lshlrev_b32_e32 v142, 16, v139
	v_and_b32_e32 v145, 0xffff0000, v139
	v_lshlrev_b32_e32 v138, 16, v140
	v_and_b32_e32 v139, 0xffff0000, v140
	v_lshlrev_b32_e32 v143, 16, v141
	v_and_b32_e32 v148, 0xffff0000, v141
	v_lshlrev_b32_e32 v140, 16, v134
	v_and_b32_e32 v141, 0xffff0000, v134
	v_max_f32_e32 v135, 0x1e3ce508, v135
	v_and_b32_e32 v146, 0xffff0000, v136
	v_max_f32_e32 v134, v140, v140
	v_max_f32_e32 v136, v138, v138
	v_rcp_f32_e32 v138, v135
	v_max_f32_e32 v135, v141, v141
	v_max_f32_e32 v134, 0x1e3ce508, v134
	v_max_f32_e32 v135, 0x1e3ce508, v135
	v_max_f32_e32 v141, v144, v144
	v_rcp_f32_e32 v134, v134
	v_rcp_f32_e32 v135, v135
	v_max_f32_e32 v141, 0x1e3ce508, v141
	v_lshlrev_b32_e32 v149, 16, v137
	v_max_f32_e32 v140, v142, v142
	v_rcp_f32_e32 v142, v141
	v_max_f32_e32 v141, v143, v143
	v_max_f32_e32 v4, v4, v4
	v_max_f32_e32 v5, v5, v5
	v_max_f32_e32 v144, v141, v3
	v_max_f32_e32 v141, v149, v149
	v_max_f32_e32 v4, v4, v3
	v_max_f32_e32 v5, v5, v3
	v_max_f32_e32 v141, 0x1e3ce508, v141
	v_and_b32_e32 v162, 0xffff0000, v137
	v_max_f32_e32 v137, v139, v139
	v_max_f32_e32 v139, v146, v146
	v_rcp_f32_e32 v146, v141
	v_max_f32_e32 v141, v147, v147
	v_pk_mul_f32 v[4:5], v[4:5], v[134:135]
	v_max_f32_e32 v141, 0x1e3ce508, v141
	v_pk_mul_f32 v[106:107], v[106:107], v[4:5]
	v_max_f32_e32 v4, v162, v162
	v_max_f32_e32 v139, 0x1e3ce508, v139
	v_rcp_f32_e32 v143, v141
	v_max_f32_e32 v4, 0x1e3ce508, v4
	v_rcp_f32_e32 v139, v139
	v_rcp_f32_e32 v147, v4
	v_max_f32_e32 v141, v145, v145
	v_max_f32_e32 v140, v140, v3
	v_max_f32_e32 v141, v141, v3
	v_max_f32_e32 v4, v148, v148
	v_max_f32_e32 v136, v136, v3
	v_max_f32_e32 v137, v137, v3
	v_pk_mul_f32 v[134:135], v[140:141], v[142:143]
	v_max_f32_e32 v145, v4, v3
	v_pk_mul_f32 v[108:109], v[108:109], v[134:135]
	v_pk_mul_f32 v[4:5], v[136:137], v[138:139]
	v_pk_mul_f32 v[134:135], v[144:145], v[146:147]
	v_pk_mul_f32 v[102:103], v[102:103], v[4:5]
	v_pk_mul_f32 v[104:105], v[104:105], v[134:135]
	v_lshl_add_u64 v[4:5], v[206:207], 0, s[66:67]
	v_lshl_add_u64 v[134:135], v[206:207], 0, s[28:29]
	global_load_dwordx4 v[170:173], v[4:5], off
	global_load_dwordx4 v[142:145], v[4:5], off offset:256
	global_load_dwordx4 v[162:165], v[134:135], off
	s_nop 0
	global_load_dwordx4 v[134:137], v[134:135], off offset:256
	s_waitcnt vmcnt(7)
	v_lshlrev_b32_e32 v139, 16, v168
	s_waitcnt vmcnt(5)
;     static __device__ __forceinline__ void unpack(const u32x4 g4, f32x4& g0, f32x4& g1) { g0 = (f32x4){bflo(g4.x), bfhi(g4.x), bflo(g4.y), bfhi(g4.y)}; g1 = (f32x4){bflo(g4.z), bfhi(g4.z), bflo(g4.w), bfhi(g4.w)}; }
;     __device__ __forceinline__ void mid(f32x4 (&acc)[2][2][4][2], const Unit& u, int wr, int wc, int fr, int fq, bool second) const {
;     ...
;             if (gi < 7) { const size_t row2 = r0 + ((gi + 1) >> 2) * HALF + ((gi + 1) & 3) * 16;
; #pragma unroll
;                 for (int bj = 0; bj < 2; ++bj) { gn[(gi + 1) & 1][bj] = *(const u32x4*)(GT + row2 * ldg + on + col0 + bj * HALF); gd[(gi + 1) & 1][bj] = *(const u32x4*)(GT + row2 * ldg + od + col0 + bj * HALF); } }
;             asm volatile("" ::: "memory");
; #pragma unroll
;             for (int bj = 0; bj < 2; ++bj) {
;                 f32x4 n0, n1, d0, d1; unpack(gn[gi & 1][bj], n0, n1); unpack(gd[gi & 1][bj], d0, d1);
; #pragma unroll
;                 for (int j = 0; j < 4; ++j) {
;                     acc[ai][bj][m][0][j] *= fmaxf(n0[j], nfloor) * __builtin_amdgcn_rcpf(fmaxf(d0[j], 1e-20f));
;                     acc[ai][bj][m][1][j] *= fmaxf(n1[j], nfloor) * __builtin_amdgcn_rcpf(fmaxf(d1[j], 1e-20f)); }
	v_lshlrev_b32_e32 v146, 16, v160
	v_max_f32_e32 v139, v139, v139
	v_max_f32_e32 v140, v139, v3
	v_max_f32_e32 v139, v146, v146
	v_lshlrev_b32_e32 v138, 16, v158
	v_and_b32_e32 v147, 0xffff0000, v158
	v_max_f32_e32 v139, 0x1e3ce508, v139
	v_max_f32_e32 v138, v138, v138
	v_rcp_f32_e32 v146, v139
	v_max_f32_e32 v139, v147, v147
	v_max_f32_e32 v138, 0x1e3ce508, v138
	v_max_f32_e32 v139, 0x1e3ce508, v139
	v_rcp_f32_e32 v138, v138
	v_rcp_f32_e32 v139, v139
	v_lshlrev_b32_e32 v4, 16, v166
	v_and_b32_e32 v5, 0xffff0000, v166
	v_max_f32_e32 v4, v4, v4
	v_max_f32_e32 v5, v5, v5
	v_lshlrev_b32_e32 v158, 16, v159
	v_and_b32_e32 v159, 0xffff0000, v159
	v_max_f32_e32 v4, v4, v3
	v_max_f32_e32 v5, v5, v3
	v_lshlrev_b32_e32 v148, 16, v167
	v_and_b32_e32 v149, 0xffff0000, v167
	v_lshlrev_b32_e32 v166, 16, v169
	v_and_b32_e32 v160, 0xffff0000, v160
	v_lshlrev_b32_e32 v167, 16, v161
	v_and_b32_e32 v161, 0xffff0000, v161
	v_max_f32_e32 v158, v158, v158
	v_max_f32_e32 v159, v159, v159
	v_pk_mul_f32 v[4:5], v[4:5], v[138:139]
	v_max_f32_e32 v147, v160, v160
	v_max_f32_e32 v158, 0x1e3ce508, v158
	v_max_f32_e32 v160, v166, v166
	v_max_f32_e32 v166, v167, v167
	v_max_f32_e32 v159, 0x1e3ce508, v159
	v_pk_mul_f32 v[98:99], v[98:99], v[4:5]
	v_max_f32_e32 v4, v161, v161
	v_rcp_f32_e32 v158, v158
	v_max_f32_e32 v166, 0x1e3ce508, v166
	v_rcp_f32_e32 v159, v159
	v_max_f32_e32 v4, 0x1e3ce508, v4
	v_rcp_f32_e32 v166, v166
	v_rcp_f32_e32 v167, v4
	v_and_b32_e32 v141, 0xffff0000, v168
	v_and_b32_e32 v168, 0xffff0000, v169
	v_max_f32_e32 v147, 0x1e3ce508, v147
	v_max_f32_e32 v148, v148, v148
	v_max_f32_e32 v149, v149, v149
	v_rcp_f32_e32 v147, v147
	v_max_f32_e32 v148, v148, v3
	v_max_f32_e32 v149, v149, v3
	v_max_f32_e32 v4, v168, v168
	v_max_f32_e32 v160, v160, v3
	v_pk_mul_f32 v[138:139], v[148:149], v[158:159]
	v_max_f32_e32 v161, v4, v3
	v_max_f32_e32 v141, v141, v141
	v_pk_mul_f32 v[100:101], v[100:101], v[138:139]
	v_pk_mul_f32 v[138:139], v[160:161], v[166:167]
	v_max_f32_e32 v141, v141, v3
	v_pk_mul_f32 v[96:97], v[96:97], v[138:139]
	v_lshlrev_b32_e32 v139, 16, v156
	v_pk_mul_f32 v[4:5], v[140:141], v[146:147]
	s_waitcnt vmcnt(4)
	v_lshlrev_b32_e32 v146, 16, v152
	v_max_f32_e32 v139, v139, v139
	v_max_f32_e32 v140, v139, v3
	v_max_f32_e32 v139, v146, v146
	v_lshlrev_b32_e32 v138, 16, v150
	v_and_b32_e32 v147, 0xffff0000, v150
	v_max_f32_e32 v139, 0x1e3ce508, v139
	v_max_f32_e32 v138, v138, v138
	v_rcp_f32_e32 v146, v139
	v_max_f32_e32 v139, v147, v147
	v_max_f32_e32 v138, 0x1e3ce508, v138
	v_max_f32_e32 v139, 0x1e3ce508, v139
	v_rcp_f32_e32 v138, v138
	v_rcp_f32_e32 v139, v139
	v_pk_mul_f32 v[94:95], v[94:95], v[4:5]
	v_lshlrev_b32_e32 v4, 16, v154
	v_and_b32_e32 v5, 0xffff0000, v154
	v_max_f32_e32 v4, v4, v4
	v_max_f32_e32 v5, v5, v5
	v_lshlrev_b32_e32 v150, 16, v151
	v_and_b32_e32 v151, 0xffff0000, v151
	v_max_f32_e32 v4, v4, v3
	v_max_f32_e32 v5, v5, v3
	v_lshlrev_b32_e32 v148, 16, v155
	v_and_b32_e32 v149, 0xffff0000, v155
	v_lshlrev_b32_e32 v154, 16, v157
	v_and_b32_e32 v152, 0xffff0000, v152
	v_lshlrev_b32_e32 v155, 16, v153
	v_and_b32_e32 v153, 0xffff0000, v153
	v_max_f32_e32 v150, v150, v150
	v_max_f32_e32 v151, v151, v151
	v_pk_mul_f32 v[4:5], v[4:5], v[138:139]
	v_max_f32_e32 v147, v152, v152
	v_max_f32_e32 v150, 0x1e3ce508, v150
	v_max_f32_e32 v152, v154, v154
	v_max_f32_e32 v154, v155, v155
	v_max_f32_e32 v151, 0x1e3ce508, v151
	v_pk_mul_f32 v[90:91], v[90:91], v[4:5]
	v_max_f32_e32 v4, v153, v153
	v_max_f32_e32 v147, 0x1e3ce508, v147
	v_rcp_f32_e32 v150, v150
	v_max_f32_e32 v154, 0x1e3ce508, v154
	v_rcp_f32_e32 v151, v151
	v_max_f32_e32 v4, 0x1e3ce508, v4
	v_rcp_f32_e32 v147, v147
	v_rcp_f32_e32 v154, v154
	v_rcp_f32_e32 v155, v4
	v_and_b32_e32 v141, 0xffff0000, v156
	v_and_b32_e32 v156, 0xffff0000, v157
	v_max_f32_e32 v148, v148, v148
	v_max_f32_e32 v149, v149, v149
	v_max_f32_e32 v141, v141, v141
	v_max_f32_e32 v148, v148, v3
	v_max_f32_e32 v149, v149, v3
	v_max_f32_e32 v4, v156, v156
	v_max_f32_e32 v141, v141, v3
	v_max_f32_e32 v152, v152, v3
	v_pk_mul_f32 v[138:139], v[148:149], v[150:151]
	v_max_f32_e32 v153, v4, v3
	v_pk_mul_f32 v[92:93], v[92:93], v[138:139]
	v_pk_mul_f32 v[4:5], v[140:141], v[146:147]
	v_pk_mul_f32 v[138:139], v[152:153], v[154:155]
	v_pk_mul_f32 v[86:87], v[86:87], v[4:5]
	v_pk_mul_f32 v[88:89], v[88:89], v[138:139]
	v_lshl_add_u64 v[4:5], v[208:209], 0, s[66:67]
	v_lshl_add_u64 v[138:139], v[208:209], 0, s[28:29]
	s_waitcnt vmcnt(3)
	v_lshlrev_b32_e32 v155, 16, v172
	global_load_dwordx4 v[158:161], v[4:5], off
	global_load_dwordx4 v[146:149], v[4:5], off offset:256
	global_load_dwordx4 v[150:153], v[138:139], off
	s_nop 0
	global_load_dwordx4 v[138:141], v[138:139], off offset:256
	s_waitcnt vmcnt(5)
;     static __device__ __forceinline__ void unpack(const u32x4 g4, f32x4& g0, f32x4& g1) { g0 = (f32x4){bflo(g4.x), bfhi(g4.x), bflo(g4.y), bfhi(g4.y)}; g1 = (f32x4){bflo(g4.z), bfhi(g4.z), bflo(g4.w), bfhi(g4.w)}; }
;     __device__ __forceinline__ void mid(f32x4 (&acc)[2][2][4][2], const Unit& u, int wr, int wc, int fr, int fq, bool second) const {
;     ...
;             if (gi < 7) { const size_t row2 = r0 + ((gi + 1) >> 2) * HALF + ((gi + 1) & 3) * 16;
; #pragma unroll
;                 for (int bj = 0; bj < 2; ++bj) { gn[(gi + 1) & 1][bj] = *(const u32x4*)(GT + row2 * ldg + on + col0 + bj * HALF); gd[(gi + 1) & 1][bj] = *(const u32x4*)(GT + row2 * ldg + od + col0 + bj * HALF); } }
;             asm volatile("" ::: "memory");
; #pragma unroll
;             for (int bj = 0; bj < 2; ++bj) {
;                 f32x4 n0, n1, d0, d1; unpack(gn[gi & 1][bj], n0, n1); unpack(gd[gi & 1][bj], d0, d1);
; #pragma unroll
;                 for (int j = 0; j < 4; ++j) {
;                     acc[ai][bj][m][0][j] *= fmaxf(n0[j], nfloor) * __builtin_amdgcn_rcpf(fmaxf(d0[j], 1e-20f));
;                     acc[ai][bj][m][1][j] *= fmaxf(n1[j], nfloor) * __builtin_amdgcn_rcpf(fmaxf(d1[j], 1e-20f)); }
	v_lshlrev_b32_e32 v154, 16, v162
	v_and_b32_e32 v168, 0xffff0000, v162
	v_lshlrev_b32_e32 v162, 16, v164
	v_max_f32_e32 v155, v155, v155
	v_max_f32_e32 v156, v155, v3
	v_max_f32_e32 v155, v162, v162
	v_max_f32_e32 v155, 0x1e3ce508, v155
	v_lshlrev_b32_e32 v4, 16, v170
	v_and_b32_e32 v5, 0xffff0000, v170
	v_lshlrev_b32_e32 v170, 16, v163
	v_max_f32_e32 v154, v154, v154
	v_rcp_f32_e32 v162, v155
	v_max_f32_e32 v155, v168, v168
	v_and_b32_e32 v157, 0xffff0000, v172
	v_lshlrev_b32_e32 v167, 16, v173
	v_and_b32_e32 v172, 0xffff0000, v173
	v_lshlrev_b32_e32 v173, 16, v165
	v_and_b32_e32 v185, 0xffff0000, v165
	v_max_f32_e32 v154, 0x1e3ce508, v154
	v_max_f32_e32 v155, 0x1e3ce508, v155
	v_max_f32_e32 v165, v170, v170
	v_lshlrev_b32_e32 v166, 16, v171
	v_rcp_f32_e32 v154, v154
	v_rcp_f32_e32 v155, v155
	v_max_f32_e32 v165, 0x1e3ce508, v165
	v_and_b32_e32 v169, 0xffff0000, v171
	v_and_b32_e32 v171, 0xffff0000, v163
	v_and_b32_e32 v163, 0xffff0000, v164
	v_max_f32_e32 v164, v166, v166
	v_rcp_f32_e32 v166, v165
	v_max_f32_e32 v165, v167, v167
	v_max_f32_e32 v4, v4, v4
	v_max_f32_e32 v5, v5, v5
	v_max_f32_e32 v168, v165, v3
	v_max_f32_e32 v165, v173, v173
	v_max_f32_e32 v4, v4, v3
	v_max_f32_e32 v5, v5, v3
	v_max_f32_e32 v165, 0x1e3ce508, v165
	v_max_f32_e32 v163, v163, v163
	v_rcp_f32_e32 v170, v165
	v_max_f32_e32 v165, v171, v171
	v_pk_mul_f32 v[4:5], v[4:5], v[154:155]
	v_max_f32_e32 v163, 0x1e3ce508, v163
	v_max_f32_e32 v165, 0x1e3ce508, v165
	v_pk_mul_f32 v[82:83], v[82:83], v[4:5]
	v_max_f32_e32 v4, v185, v185
	v_rcp_f32_e32 v163, v163
	v_rcp_f32_e32 v167, v165
	v_max_f32_e32 v4, 0x1e3ce508, v4
	v_rcp_f32_e32 v171, v4
	v_max_f32_e32 v157, v157, v157
	v_max_f32_e32 v165, v169, v169
	v_max_f32_e32 v157, v157, v3
	v_max_f32_e32 v164, v164, v3
	v_max_f32_e32 v165, v165, v3
	v_max_f32_e32 v4, v172, v172
	v_pk_mul_f32 v[154:155], v[164:165], v[166:167]
	v_max_f32_e32 v169, v4, v3
	v_pk_mul_f32 v[4:5], v[156:157], v[162:163]
	s_waitcnt vmcnt(4)
	v_lshlrev_b32_e32 v156, 16, v135
	v_and_b32_e32 v163, 0xffff0000, v135
	v_lshlrev_b32_e32 v135, 16, v136
	v_pk_mul_f32 v[84:85], v[84:85], v[154:155]
	v_pk_mul_f32 v[154:155], v[168:169], v[170:171]
	v_max_f32_e32 v135, v135, v135
	v_pk_mul_f32 v[80:81], v[80:81], v[154:155]
	v_pk_mul_f32 v[78:79], v[78:79], v[4:5]
	v_lshlrev_b32_e32 v4, 16, v142
	v_and_b32_e32 v5, 0xffff0000, v142
	v_lshlrev_b32_e32 v154, 16, v143
	v_and_b32_e32 v157, 0xffff0000, v143
	v_lshlrev_b32_e32 v142, 16, v144
	v_and_b32_e32 v143, 0xffff0000, v144
	v_lshlrev_b32_e32 v155, 16, v145
	v_and_b32_e32 v164, 0xffff0000, v145
	v_lshlrev_b32_e32 v144, 16, v134
	v_and_b32_e32 v145, 0xffff0000, v134
	v_max_f32_e32 v135, 0x1e3ce508, v135
	v_and_b32_e32 v162, 0xffff0000, v136
	v_max_f32_e32 v134, v144, v144
	v_max_f32_e32 v136, v142, v142
	v_rcp_f32_e32 v142, v135
	v_max_f32_e32 v135, v145, v145
	v_max_f32_e32 v134, 0x1e3ce508, v134
	v_max_f32_e32 v135, 0x1e3ce508, v135
	v_max_f32_e32 v145, v156, v156
	v_rcp_f32_e32 v134, v134
	v_rcp_f32_e32 v135, v135
	v_max_f32_e32 v145, 0x1e3ce508, v145
	v_lshlrev_b32_e32 v165, 16, v137
	v_max_f32_e32 v144, v154, v154
	v_rcp_f32_e32 v154, v145
	v_max_f32_e32 v145, v155, v155
	v_max_f32_e32 v4, v4, v4
	v_max_f32_e32 v5, v5, v5
	v_max_f32_e32 v156, v145, v3
	v_max_f32_e32 v145, v165, v165
	v_max_f32_e32 v4, v4, v3
	v_max_f32_e32 v5, v5, v3
	v_max_f32_e32 v145, 0x1e3ce508, v145
	v_and_b32_e32 v166, 0xffff0000, v137
	v_max_f32_e32 v137, v143, v143
	v_max_f32_e32 v143, v162, v162
	v_rcp_f32_e32 v162, v145
	v_max_f32_e32 v145, v163, v163
	v_pk_mul_f32 v[4:5], v[4:5], v[134:135]
	v_max_f32_e32 v145, 0x1e3ce508, v145
	v_pk_mul_f32 v[74:75], v[74:75], v[4:5]
	v_max_f32_e32 v4, v166, v166
	v_max_f32_e32 v143, 0x1e3ce508, v143
	v_rcp_f32_e32 v155, v145
	v_max_f32_e32 v4, 0x1e3ce508, v4
	v_rcp_f32_e32 v143, v143
	v_rcp_f32_e32 v163, v4
	v_max_f32_e32 v145, v157, v157
	v_max_f32_e32 v144, v144, v3
	v_max_f32_e32 v145, v145, v3
	v_max_f32_e32 v4, v164, v164
	v_max_f32_e32 v136, v136, v3
	v_max_f32_e32 v137, v137, v3
	v_pk_mul_f32 v[134:135], v[144:145], v[154:155]
	v_max_f32_e32 v157, v4, v3
	v_pk_mul_f32 v[76:77], v[76:77], v[134:135]
	v_pk_mul_f32 v[4:5], v[136:137], v[142:143]
	v_pk_mul_f32 v[134:135], v[156:157], v[162:163]
	v_pk_mul_f32 v[70:71], v[70:71], v[4:5]
	v_pk_mul_f32 v[72:73], v[72:73], v[134:135]
	v_lshl_add_u64 v[4:5], v[210:211], 0, s[66:67]
	v_lshl_add_u64 v[134:135], v[210:211], 0, s[28:29]
	global_load_dwordx4 v[162:165], v[4:5], off
	global_load_dwordx4 v[142:145], v[4:5], off offset:256
	global_load_dwordx4 v[154:157], v[134:135], off
	s_nop 0
	global_load_dwordx4 v[134:137], v[134:135], off offset:256
	s_waitcnt vmcnt(5)
;     static __device__ __forceinline__ void unpack(const u32x4 g4, f32x4& g0, f32x4& g1) { g0 = (f32x4){bflo(g4.x), bfhi(g4.x), bflo(g4.y), bfhi(g4.y)}; g1 = (f32x4){bflo(g4.z), bfhi(g4.z), bflo(g4.w), bfhi(g4.w)}; }
;     __device__ __forceinline__ void mid(f32x4 (&acc)[2][2][4][2], const Unit& u, int wr, int wc, int fr, int fq, bool second) const {
;     ...
;             if (gi < 7) { const size_t row2 = r0 + ((gi + 1) >> 2) * HALF + ((gi + 1) & 3) * 16;
; #pragma unroll
;                 for (int bj = 0; bj < 2; ++bj) { gn[(gi + 1) & 1][bj] = *(const u32x4*)(GT + row2 * ldg + on + col0 + bj * HALF); gd[(gi + 1) & 1][bj] = *(const u32x4*)(GT + row2 * ldg + od + col0 + bj * HALF); } }
;             asm volatile("" ::: "memory");
; #pragma unroll
;             for (int bj = 0; bj < 2; ++bj) {
;                 f32x4 n0, n1, d0, d1; unpack(gn[gi & 1][bj], n0, n1); unpack(gd[gi & 1][bj], d0, d1);
; #pragma unroll
;                 for (int j = 0; j < 4; ++j) {
;                     acc[ai][bj][m][0][j] *= fmaxf(n0[j], nfloor) * __builtin_amdgcn_rcpf(fmaxf(d0[j], 1e-20f));
;                     acc[ai][bj][m][1][j] *= fmaxf(n1[j], nfloor) * __builtin_amdgcn_rcpf(fmaxf(d1[j], 1e-20f)); }
	v_lshlrev_b32_e32 v168, 16, v151
	v_and_b32_e32 v171, 0xffff0000, v151
	v_lshlrev_b32_e32 v151, 16, v152
	v_max_f32_e32 v151, v151, v151
	v_lshlrev_b32_e32 v4, 16, v158
	v_and_b32_e32 v5, 0xffff0000, v158
	v_lshlrev_b32_e32 v166, 16, v159
	v_and_b32_e32 v169, 0xffff0000, v159
	v_lshlrev_b32_e32 v158, 16, v160
	v_and_b32_e32 v159, 0xffff0000, v160
	v_lshlrev_b32_e32 v167, 16, v161
	v_and_b32_e32 v172, 0xffff0000, v161
	v_lshlrev_b32_e32 v160, 16, v150
	v_and_b32_e32 v161, 0xffff0000, v150
	v_max_f32_e32 v151, 0x1e3ce508, v151
	v_and_b32_e32 v170, 0xffff0000, v152
	v_max_f32_e32 v150, v160, v160
	v_max_f32_e32 v152, v158, v158
	v_rcp_f32_e32 v158, v151
	v_max_f32_e32 v151, v161, v161
	v_max_f32_e32 v150, 0x1e3ce508, v150
	v_max_f32_e32 v151, 0x1e3ce508, v151
	v_max_f32_e32 v161, v168, v168
	v_rcp_f32_e32 v150, v150
	v_rcp_f32_e32 v151, v151
	v_max_f32_e32 v161, 0x1e3ce508, v161
	v_lshlrev_b32_e32 v173, 16, v153
	v_max_f32_e32 v160, v166, v166
	v_rcp_f32_e32 v166, v161
	v_max_f32_e32 v161, v167, v167
	v_max_f32_e32 v4, v4, v4
	v_max_f32_e32 v5, v5, v5
	v_max_f32_e32 v168, v161, v3
	v_max_f32_e32 v161, v173, v173
	v_max_f32_e32 v4, v4, v3
	v_max_f32_e32 v5, v5, v3
	v_max_f32_e32 v161, 0x1e3ce508, v161
	v_and_b32_e32 v185, 0xffff0000, v153
	v_max_f32_e32 v153, v159, v159
	v_max_f32_e32 v159, v170, v170
	v_rcp_f32_e32 v170, v161
	v_max_f32_e32 v161, v171, v171
	v_pk_mul_f32 v[4:5], v[4:5], v[150:151]
	v_max_f32_e32 v159, 0x1e3ce508, v159
	v_max_f32_e32 v161, 0x1e3ce508, v161
	v_pk_mul_f32 v[66:67], v[66:67], v[4:5]
	v_max_f32_e32 v4, v185, v185
	v_rcp_f32_e32 v159, v159
	v_rcp_f32_e32 v167, v161
	v_max_f32_e32 v4, 0x1e3ce508, v4
	v_rcp_f32_e32 v171, v4
	v_max_f32_e32 v161, v169, v169
	v_max_f32_e32 v152, v152, v3
	v_max_f32_e32 v153, v153, v3
	v_max_f32_e32 v160, v160, v3
	v_max_f32_e32 v161, v161, v3
	v_max_f32_e32 v4, v172, v172
	v_pk_mul_f32 v[150:151], v[160:161], v[166:167]
	v_max_f32_e32 v169, v4, v3
	v_pk_mul_f32 v[4:5], v[152:153], v[158:159]
	s_waitcnt vmcnt(4)
	v_lshlrev_b32_e32 v152, 16, v139
	v_and_b32_e32 v159, 0xffff0000, v139
	v_lshlrev_b32_e32 v139, 16, v140
	v_pk_mul_f32 v[68:69], v[68:69], v[150:151]
	v_pk_mul_f32 v[150:151], v[168:169], v[170:171]
	v_max_f32_e32 v139, v139, v139
	v_pk_mul_f32 v[64:65], v[64:65], v[150:151]
	v_pk_mul_f32 v[62:63], v[62:63], v[4:5]
	v_lshlrev_b32_e32 v4, 16, v146
	v_and_b32_e32 v5, 0xffff0000, v146
	v_lshlrev_b32_e32 v150, 16, v147
	v_and_b32_e32 v153, 0xffff0000, v147
	v_lshlrev_b32_e32 v146, 16, v148
	v_and_b32_e32 v147, 0xffff0000, v148
	v_lshlrev_b32_e32 v151, 16, v149
	v_and_b32_e32 v160, 0xffff0000, v149
	v_lshlrev_b32_e32 v148, 16, v138
	v_and_b32_e32 v149, 0xffff0000, v138
	v_max_f32_e32 v139, 0x1e3ce508, v139
	v_and_b32_e32 v158, 0xffff0000, v140
	v_max_f32_e32 v138, v148, v148
	v_max_f32_e32 v140, v146, v146
	v_rcp_f32_e32 v146, v139
	v_max_f32_e32 v139, v149, v149
	v_max_f32_e32 v138, 0x1e3ce508, v138
	v_max_f32_e32 v139, 0x1e3ce508, v139
	v_max_f32_e32 v149, v152, v152
	v_rcp_f32_e32 v138, v138
	v_rcp_f32_e32 v139, v139
	v_max_f32_e32 v149, 0x1e3ce508, v149
	v_lshlrev_b32_e32 v161, 16, v141
	v_max_f32_e32 v148, v150, v150
	v_rcp_f32_e32 v150, v149
	v_max_f32_e32 v149, v151, v151
	v_max_f32_e32 v4, v4, v4
	v_max_f32_e32 v5, v5, v5
	v_max_f32_e32 v152, v149, v3
	v_max_f32_e32 v149, v161, v161
	v_max_f32_e32 v4, v4, v3
	v_max_f32_e32 v5, v5, v3
	v_max_f32_e32 v149, 0x1e3ce508, v149
	v_and_b32_e32 v166, 0xffff0000, v141
	v_max_f32_e32 v141, v147, v147
	v_max_f32_e32 v147, v158, v158
	v_rcp_f32_e32 v158, v149
	v_max_f32_e32 v149, v159, v159
	v_pk_mul_f32 v[4:5], v[4:5], v[138:139]
	v_max_f32_e32 v149, 0x1e3ce508, v149
	v_pk_mul_f32 v[58:59], v[58:59], v[4:5]
	v_max_f32_e32 v4, v166, v166
	v_max_f32_e32 v147, 0x1e3ce508, v147
	v_rcp_f32_e32 v151, v149
	v_max_f32_e32 v4, 0x1e3ce508, v4
	v_rcp_f32_e32 v147, v147
	v_rcp_f32_e32 v159, v4
	v_max_f32_e32 v149, v153, v153
	v_max_f32_e32 v148, v148, v3
	v_max_f32_e32 v149, v149, v3
	v_max_f32_e32 v4, v160, v160
	v_max_f32_e32 v140, v140, v3
	v_max_f32_e32 v141, v141, v3
	v_pk_mul_f32 v[138:139], v[148:149], v[150:151]
	v_max_f32_e32 v153, v4, v3
	v_pk_mul_f32 v[60:61], v[60:61], v[138:139]
	v_pk_mul_f32 v[4:5], v[140:141], v[146:147]
	v_pk_mul_f32 v[138:139], v[152:153], v[158:159]
	v_pk_mul_f32 v[54:55], v[54:55], v[4:5]
	v_pk_mul_f32 v[56:57], v[56:57], v[138:139]
	v_lshl_add_u64 v[4:5], v[212:213], 0, s[66:67]
	v_lshl_add_u64 v[138:139], v[212:213], 0, s[28:29]
	global_load_dwordx4 v[158:161], v[4:5], off
	global_load_dwordx4 v[146:149], v[4:5], off offset:256
	global_load_dwordx4 v[150:153], v[138:139], off
	s_nop 0
	global_load_dwordx4 v[138:141], v[138:139], off offset:256
	s_waitcnt vmcnt(5)
;     static __device__ __forceinline__ void unpack(const u32x4 g4, f32x4& g0, f32x4& g1) { g0 = (f32x4){bflo(g4.x), bfhi(g4.x), bflo(g4.y), bfhi(g4.y)}; g1 = (f32x4){bflo(g4.z), bfhi(g4.z), bflo(g4.w), bfhi(g4.w)}; }
;     __device__ __forceinline__ void mid(f32x4 (&acc)[2][2][4][2], const Unit& u, int wr, int wc, int fr, int fq, bool second) const {
;     ...
;             if (gi < 7) { const size_t row2 = r0 + ((gi + 1) >> 2) * HALF + ((gi + 1) & 3) * 16;
; #pragma unroll
;                 for (int bj = 0; bj < 2; ++bj) { gn[(gi + 1) & 1][bj] = *(const u32x4*)(GT + row2 * ldg + on + col0 + bj * HALF); gd[(gi + 1) & 1][bj] = *(const u32x4*)(GT + row2 * ldg + od + col0 + bj * HALF); } }
;             asm volatile("" ::: "memory");
; #pragma unroll
;             for (int bj = 0; bj < 2; ++bj) {
;                 f32x4 n0, n1, d0, d1; unpack(gn[gi & 1][bj], n0, n1); unpack(gd[gi & 1][bj], d0, d1);
; #pragma unroll
;                 for (int j = 0; j < 4; ++j) {
;                     acc[ai][bj][m][0][j] *= fmaxf(n0[j], nfloor) * __builtin_amdgcn_rcpf(fmaxf(d0[j], 1e-20f));
;                     acc[ai][bj][m][1][j] *= fmaxf(n1[j], nfloor) * __builtin_amdgcn_rcpf(fmaxf(d1[j], 1e-20f)); }
	v_lshlrev_b32_e32 v168, 16, v155
	v_and_b32_e32 v171, 0xffff0000, v155
	v_lshlrev_b32_e32 v155, 16, v156
	v_max_f32_e32 v155, v155, v155
	v_lshlrev_b32_e32 v4, 16, v162
	v_and_b32_e32 v5, 0xffff0000, v162
	v_lshlrev_b32_e32 v166, 16, v163
	v_and_b32_e32 v169, 0xffff0000, v163
	v_lshlrev_b32_e32 v162, 16, v164
	v_and_b32_e32 v163, 0xffff0000, v164
	v_lshlrev_b32_e32 v167, 16, v165
	v_and_b32_e32 v172, 0xffff0000, v165
	v_lshlrev_b32_e32 v164, 16, v154
	v_and_b32_e32 v165, 0xffff0000, v154
	v_max_f32_e32 v155, 0x1e3ce508, v155
	v_and_b32_e32 v170, 0xffff0000, v156
	v_max_f32_e32 v154, v164, v164
	v_max_f32_e32 v156, v162, v162
	v_rcp_f32_e32 v162, v155
	v_max_f32_e32 v155, v165, v165
	v_max_f32_e32 v154, 0x1e3ce508, v154
	v_max_f32_e32 v155, 0x1e3ce508, v155
	v_max_f32_e32 v165, v168, v168
	v_rcp_f32_e32 v154, v154
	v_rcp_f32_e32 v155, v155
	v_max_f32_e32 v165, 0x1e3ce508, v165
	v_lshlrev_b32_e32 v173, 16, v157
	v_max_f32_e32 v164, v166, v166
	v_rcp_f32_e32 v166, v165
	v_max_f32_e32 v165, v167, v167
	v_max_f32_e32 v4, v4, v4
	v_max_f32_e32 v5, v5, v5
	v_max_f32_e32 v168, v165, v3
	v_max_f32_e32 v165, v173, v173
	v_max_f32_e32 v4, v4, v3
	v_max_f32_e32 v5, v5, v3
	v_max_f32_e32 v165, 0x1e3ce508, v165
	v_and_b32_e32 v185, 0xffff0000, v157
	v_max_f32_e32 v157, v163, v163
	v_max_f32_e32 v163, v170, v170
	v_rcp_f32_e32 v170, v165
	v_max_f32_e32 v165, v171, v171
	v_pk_mul_f32 v[4:5], v[4:5], v[154:155]
	v_max_f32_e32 v163, 0x1e3ce508, v163
	v_max_f32_e32 v165, 0x1e3ce508, v165
	v_pk_mul_f32 v[50:51], v[50:51], v[4:5]
	v_max_f32_e32 v4, v185, v185
	v_rcp_f32_e32 v163, v163
	v_rcp_f32_e32 v167, v165
	v_max_f32_e32 v4, 0x1e3ce508, v4
	v_rcp_f32_e32 v171, v4
	v_max_f32_e32 v165, v169, v169
	v_max_f32_e32 v156, v156, v3
	v_max_f32_e32 v157, v157, v3
	v_max_f32_e32 v164, v164, v3
	v_max_f32_e32 v165, v165, v3
	v_max_f32_e32 v4, v172, v172
	v_pk_mul_f32 v[154:155], v[164:165], v[166:167]
	v_max_f32_e32 v169, v4, v3
	v_pk_mul_f32 v[4:5], v[156:157], v[162:163]
	s_waitcnt vmcnt(4)
	v_lshlrev_b32_e32 v156, 16, v135
	v_and_b32_e32 v163, 0xffff0000, v135
	v_lshlrev_b32_e32 v135, 16, v136
	v_pk_mul_f32 v[52:53], v[52:53], v[154:155]
	v_pk_mul_f32 v[154:155], v[168:169], v[170:171]
	v_max_f32_e32 v135, v135, v135
	v_pk_mul_f32 v[48:49], v[48:49], v[154:155]
	v_pk_mul_f32 v[46:47], v[46:47], v[4:5]
	v_lshlrev_b32_e32 v4, 16, v142
	v_and_b32_e32 v5, 0xffff0000, v142
	v_lshlrev_b32_e32 v154, 16, v143
	v_and_b32_e32 v157, 0xffff0000, v143
	v_lshlrev_b32_e32 v142, 16, v144
	v_and_b32_e32 v143, 0xffff0000, v144
	v_lshlrev_b32_e32 v155, 16, v145
	v_and_b32_e32 v164, 0xffff0000, v145
	v_lshlrev_b32_e32 v144, 16, v134
	v_and_b32_e32 v145, 0xffff0000, v134
	v_max_f32_e32 v135, 0x1e3ce508, v135
	v_and_b32_e32 v162, 0xffff0000, v136
	v_max_f32_e32 v134, v144, v144
	v_max_f32_e32 v136, v142, v142
	v_rcp_f32_e32 v142, v135
	v_max_f32_e32 v135, v145, v145
	v_max_f32_e32 v134, 0x1e3ce508, v134
	v_max_f32_e32 v135, 0x1e3ce508, v135
	v_max_f32_e32 v145, v156, v156
	v_rcp_f32_e32 v134, v134
	v_rcp_f32_e32 v135, v135
	v_max_f32_e32 v145, 0x1e3ce508, v145
	v_lshlrev_b32_e32 v165, 16, v137
	v_max_f32_e32 v144, v154, v154
	v_rcp_f32_e32 v154, v145
	v_max_f32_e32 v145, v155, v155
	v_max_f32_e32 v4, v4, v4
	v_max_f32_e32 v5, v5, v5
	v_max_f32_e32 v156, v145, v3
	v_max_f32_e32 v145, v165, v165
	v_max_f32_e32 v4, v4, v3
	v_max_f32_e32 v5, v5, v3
	v_max_f32_e32 v145, 0x1e3ce508, v145
	v_and_b32_e32 v166, 0xffff0000, v137
	v_max_f32_e32 v137, v143, v143
	v_max_f32_e32 v143, v162, v162
	v_rcp_f32_e32 v162, v145
	v_max_f32_e32 v145, v163, v163
	v_pk_mul_f32 v[4:5], v[4:5], v[134:135]
	v_max_f32_e32 v145, 0x1e3ce508, v145
	v_pk_mul_f32 v[42:43], v[42:43], v[4:5]
	v_max_f32_e32 v4, v166, v166
	v_max_f32_e32 v143, 0x1e3ce508, v143
	v_rcp_f32_e32 v155, v145
	v_max_f32_e32 v4, 0x1e3ce508, v4
	v_rcp_f32_e32 v143, v143
	v_rcp_f32_e32 v163, v4
	v_max_f32_e32 v145, v157, v157
	v_max_f32_e32 v144, v144, v3
	v_max_f32_e32 v145, v145, v3
	v_max_f32_e32 v4, v164, v164
	v_max_f32_e32 v136, v136, v3
	v_max_f32_e32 v137, v137, v3
	v_pk_mul_f32 v[134:135], v[144:145], v[154:155]
	v_max_f32_e32 v157, v4, v3
	v_pk_mul_f32 v[44:45], v[44:45], v[134:135]
	v_pk_mul_f32 v[4:5], v[136:137], v[142:143]
	v_pk_mul_f32 v[134:135], v[156:157], v[162:163]
	v_pk_mul_f32 v[38:39], v[38:39], v[4:5]
	v_pk_mul_f32 v[40:41], v[40:41], v[134:135]
	v_lshl_add_u64 v[4:5], v[214:215], 0, s[66:67]
	v_lshl_add_u64 v[134:135], v[214:215], 0, s[28:29]
	global_load_dwordx4 v[162:165], v[4:5], off
	global_load_dwordx4 v[142:145], v[4:5], off offset:256
	global_load_dwordx4 v[154:157], v[134:135], off
	s_nop 0
	global_load_dwordx4 v[134:137], v[134:135], off offset:256
	s_waitcnt vmcnt(5)
;     static __device__ __forceinline__ void unpack(const u32x4 g4, f32x4& g0, f32x4& g1) { g0 = (f32x4){bflo(g4.x), bfhi(g4.x), bflo(g4.y), bfhi(g4.y)}; g1 = (f32x4){bflo(g4.z), bfhi(g4.z), bflo(g4.w), bfhi(g4.w)}; }
;     __device__ __forceinline__ void mid(f32x4 (&acc)[2][2][4][2], const Unit& u, int wr, int wc, int fr, int fq, bool second) const {
;     ...
;             if (gi < 7) { const size_t row2 = r0 + ((gi + 1) >> 2) * HALF + ((gi + 1) & 3) * 16;
; #pragma unroll
;                 for (int bj = 0; bj < 2; ++bj) { gn[(gi + 1) & 1][bj] = *(const u32x4*)(GT + row2 * ldg + on + col0 + bj * HALF); gd[(gi + 1) & 1][bj] = *(const u32x4*)(GT + row2 * ldg + od + col0 + bj * HALF); } }
;             asm volatile("" ::: "memory");
; #pragma unroll
;             for (int bj = 0; bj < 2; ++bj) {
;                 f32x4 n0, n1, d0, d1; unpack(gn[gi & 1][bj], n0, n1); unpack(gd[gi & 1][bj], d0, d1);
; #pragma unroll
;                 for (int j = 0; j < 4; ++j) {
;                     acc[ai][bj][m][0][j] *= fmaxf(n0[j], nfloor) * __builtin_amdgcn_rcpf(fmaxf(d0[j], 1e-20f));
;                     acc[ai][bj][m][1][j] *= fmaxf(n1[j], nfloor) * __builtin_amdgcn_rcpf(fmaxf(d1[j], 1e-20f)); }
	v_lshlrev_b32_e32 v168, 16, v151
	v_and_b32_e32 v171, 0xffff0000, v151
	v_lshlrev_b32_e32 v151, 16, v152
	v_max_f32_e32 v151, v151, v151
	v_lshlrev_b32_e32 v4, 16, v158
	v_and_b32_e32 v5, 0xffff0000, v158
	v_lshlrev_b32_e32 v166, 16, v159
	v_and_b32_e32 v169, 0xffff0000, v159
	v_lshlrev_b32_e32 v158, 16, v160
	v_and_b32_e32 v159, 0xffff0000, v160
	v_lshlrev_b32_e32 v167, 16, v161
	v_and_b32_e32 v172, 0xffff0000, v161
	v_lshlrev_b32_e32 v160, 16, v150
	v_and_b32_e32 v161, 0xffff0000, v150
	v_max_f32_e32 v151, 0x1e3ce508, v151
	v_and_b32_e32 v170, 0xffff0000, v152
	v_max_f32_e32 v150, v160, v160
	v_max_f32_e32 v152, v158, v158
	v_rcp_f32_e32 v158, v151
	v_max_f32_e32 v151, v161, v161
	v_max_f32_e32 v150, 0x1e3ce508, v150
	v_max_f32_e32 v151, 0x1e3ce508, v151
	v_max_f32_e32 v161, v168, v168
	v_rcp_f32_e32 v150, v150
	v_rcp_f32_e32 v151, v151
	v_max_f32_e32 v161, 0x1e3ce508, v161
	v_lshlrev_b32_e32 v173, 16, v153
	v_max_f32_e32 v160, v166, v166
	v_rcp_f32_e32 v166, v161
	v_max_f32_e32 v161, v167, v167
	v_max_f32_e32 v4, v4, v4
	v_max_f32_e32 v5, v5, v5
	v_max_f32_e32 v168, v161, v3
	v_max_f32_e32 v161, v173, v173
	v_max_f32_e32 v4, v4, v3
	v_max_f32_e32 v5, v5, v3
	v_max_f32_e32 v161, 0x1e3ce508, v161
	v_and_b32_e32 v185, 0xffff0000, v153
	v_max_f32_e32 v153, v159, v159
	v_max_f32_e32 v159, v170, v170
	v_rcp_f32_e32 v170, v161
	v_max_f32_e32 v161, v171, v171
	v_pk_mul_f32 v[4:5], v[4:5], v[150:151]
	v_max_f32_e32 v159, 0x1e3ce508, v159
	v_max_f32_e32 v161, 0x1e3ce508, v161
	v_pk_mul_f32 v[34:35], v[34:35], v[4:5]
	v_max_f32_e32 v4, v185, v185
	v_rcp_f32_e32 v159, v159
	v_rcp_f32_e32 v167, v161
	v_max_f32_e32 v4, 0x1e3ce508, v4
	v_rcp_f32_e32 v171, v4
	v_max_f32_e32 v161, v169, v169
	v_max_f32_e32 v152, v152, v3
	v_max_f32_e32 v153, v153, v3
	v_max_f32_e32 v160, v160, v3
	v_max_f32_e32 v161, v161, v3
	v_max_f32_e32 v4, v172, v172
	v_pk_mul_f32 v[150:151], v[160:161], v[166:167]
	v_max_f32_e32 v169, v4, v3
	v_pk_mul_f32 v[4:5], v[152:153], v[158:159]
	s_waitcnt vmcnt(4)
	v_lshlrev_b32_e32 v152, 16, v139
	v_and_b32_e32 v159, 0xffff0000, v139
	v_lshlrev_b32_e32 v139, 16, v140
	v_pk_mul_f32 v[36:37], v[36:37], v[150:151]
	v_pk_mul_f32 v[150:151], v[168:169], v[170:171]
	v_max_f32_e32 v139, v139, v139
	v_pk_mul_f32 v[32:33], v[32:33], v[150:151]
	v_pk_mul_f32 v[30:31], v[30:31], v[4:5]
	v_lshlrev_b32_e32 v4, 16, v146
	v_and_b32_e32 v5, 0xffff0000, v146
	v_lshlrev_b32_e32 v150, 16, v147
	v_and_b32_e32 v153, 0xffff0000, v147
	v_lshlrev_b32_e32 v146, 16, v148
	v_and_b32_e32 v147, 0xffff0000, v148
	v_lshlrev_b32_e32 v151, 16, v149
	v_and_b32_e32 v160, 0xffff0000, v149
	v_lshlrev_b32_e32 v148, 16, v138
	v_and_b32_e32 v149, 0xffff0000, v138
	v_max_f32_e32 v139, 0x1e3ce508, v139
	v_and_b32_e32 v158, 0xffff0000, v140
	v_max_f32_e32 v138, v148, v148
	v_max_f32_e32 v140, v146, v146
	v_rcp_f32_e32 v146, v139
	v_max_f32_e32 v139, v149, v149
	v_max_f32_e32 v138, 0x1e3ce508, v138
	v_max_f32_e32 v139, 0x1e3ce508, v139
	v_max_f32_e32 v149, v152, v152
	v_rcp_f32_e32 v138, v138
	v_rcp_f32_e32 v139, v139
	v_max_f32_e32 v149, 0x1e3ce508, v149
	v_lshlrev_b32_e32 v161, 16, v141
	v_max_f32_e32 v148, v150, v150
	v_rcp_f32_e32 v150, v149
	v_max_f32_e32 v149, v151, v151
	v_max_f32_e32 v4, v4, v4
	v_max_f32_e32 v5, v5, v5
	v_max_f32_e32 v152, v149, v3
	v_max_f32_e32 v149, v161, v161
	v_max_f32_e32 v4, v4, v3
	v_max_f32_e32 v5, v5, v3
	v_max_f32_e32 v149, 0x1e3ce508, v149
	v_and_b32_e32 v166, 0xffff0000, v141
	v_max_f32_e32 v141, v147, v147
	v_max_f32_e32 v147, v158, v158
	v_rcp_f32_e32 v158, v149
	v_max_f32_e32 v149, v159, v159
	v_pk_mul_f32 v[4:5], v[4:5], v[138:139]
	v_max_f32_e32 v149, 0x1e3ce508, v149
	v_pk_mul_f32 v[26:27], v[26:27], v[4:5]
	v_max_f32_e32 v4, v166, v166
	v_rcp_f32_e32 v151, v149
	v_max_f32_e32 v4, 0x1e3ce508, v4
	v_rcp_f32_e32 v159, v4
	v_max_f32_e32 v147, 0x1e3ce508, v147
	v_max_f32_e32 v149, v153, v153
	v_rcp_f32_e32 v147, v147
	v_max_f32_e32 v148, v148, v3
	v_max_f32_e32 v149, v149, v3
	v_max_f32_e32 v4, v160, v160
	v_pk_mul_f32 v[138:139], v[148:149], v[150:151]
	v_max_f32_e32 v153, v4, v3
	v_pk_mul_f32 v[28:29], v[28:29], v[138:139]
	v_pk_mul_f32 v[138:139], v[152:153], v[158:159]
	v_max_f32_e32 v140, v140, v3
	v_max_f32_e32 v141, v141, v3
	v_pk_mul_f32 v[24:25], v[24:25], v[138:139]
	s_waitcnt vmcnt(3)
	v_lshlrev_b32_e32 v139, 16, v164
	v_pk_mul_f32 v[4:5], v[140:141], v[146:147]
	s_waitcnt vmcnt(1)
;     static __device__ __forceinline__ void unpack(const u32x4 g4, f32x4& g0, f32x4& g1) { g0 = (f32x4){bflo(g4.x), bfhi(g4.x), bflo(g4.y), bfhi(g4.y)}; g1 = (f32x4){bflo(g4.z), bfhi(g4.z), bflo(g4.w), bfhi(g4.w)}; }
;     __device__ __forceinline__ void mid(f32x4 (&acc)[2][2][4][2], const Unit& u, int wr, int wc, int fr, int fq, bool second) const {
;     ...
;             if (gi < 7) { const size_t row2 = r0 + ((gi + 1) >> 2) * HALF + ((gi + 1) & 3) * 16;
; #pragma unroll
;                 for (int bj = 0; bj < 2; ++bj) { gn[(gi + 1) & 1][bj] = *(const u32x4*)(GT + row2 * ldg + on + col0 + bj * HALF); gd[(gi + 1) & 1][bj] = *(const u32x4*)(GT + row2 * ldg + od + col0 + bj * HALF); } }
;             asm volatile("" ::: "memory");
; #pragma unroll
;             for (int bj = 0; bj < 2; ++bj) {
;                 f32x4 n0, n1, d0, d1; unpack(gn[gi & 1][bj], n0, n1); unpack(gd[gi & 1][bj], d0, d1);
; #pragma unroll
;                 for (int j = 0; j < 4; ++j) {
;                     acc[ai][bj][m][0][j] *= fmaxf(n0[j], nfloor) * __builtin_amdgcn_rcpf(fmaxf(d0[j], 1e-20f));
;                     acc[ai][bj][m][1][j] *= fmaxf(n1[j], nfloor) * __builtin_amdgcn_rcpf(fmaxf(d1[j], 1e-20f)); }
	v_lshlrev_b32_e32 v146, 16, v156
	v_max_f32_e32 v139, v139, v139
	v_max_f32_e32 v140, v139, v3
	v_max_f32_e32 v139, v146, v146
	v_lshlrev_b32_e32 v138, 16, v154
	v_and_b32_e32 v147, 0xffff0000, v154
	v_max_f32_e32 v139, 0x1e3ce508, v139
	v_max_f32_e32 v138, v138, v138
	v_rcp_f32_e32 v146, v139
	v_max_f32_e32 v139, v147, v147
	v_max_f32_e32 v138, 0x1e3ce508, v138
	v_max_f32_e32 v139, 0x1e3ce508, v139
	v_lshlrev_b32_e32 v151, 16, v165
	v_rcp_f32_e32 v138, v138
	v_rcp_f32_e32 v139, v139
	v_pk_mul_f32 v[22:23], v[22:23], v[4:5]
	v_lshlrev_b32_e32 v4, 16, v162
	v_and_b32_e32 v5, 0xffff0000, v162
	v_and_b32_e32 v152, 0xffff0000, v156
	v_lshlrev_b32_e32 v154, 16, v157
	v_max_f32_e32 v151, v151, v151
	v_max_f32_e32 v4, v4, v4
	v_max_f32_e32 v5, v5, v5
	v_max_f32_e32 v147, v152, v152
	v_max_f32_e32 v152, v151, v3
	v_max_f32_e32 v151, v154, v154
	v_lshlrev_b32_e32 v150, 16, v155
	v_and_b32_e32 v155, 0xffff0000, v155
	v_max_f32_e32 v4, v4, v3
	v_max_f32_e32 v5, v5, v3
	v_max_f32_e32 v151, 0x1e3ce508, v151
	v_and_b32_e32 v156, 0xffff0000, v157
	v_max_f32_e32 v150, v150, v150
	v_rcp_f32_e32 v154, v151
	v_max_f32_e32 v151, v155, v155
	v_pk_mul_f32 v[4:5], v[4:5], v[138:139]
	v_max_f32_e32 v147, 0x1e3ce508, v147
	v_max_f32_e32 v150, 0x1e3ce508, v150
	v_max_f32_e32 v151, 0x1e3ce508, v151
	v_pk_mul_f32 v[18:19], v[18:19], v[4:5]
	v_max_f32_e32 v4, v156, v156
	v_rcp_f32_e32 v147, v147
	v_rcp_f32_e32 v150, v150
	v_rcp_f32_e32 v151, v151
	v_max_f32_e32 v4, 0x1e3ce508, v4
	v_lshlrev_b32_e32 v148, 16, v163
	v_and_b32_e32 v149, 0xffff0000, v163
	v_and_b32_e32 v141, 0xffff0000, v164
	v_rcp_f32_e32 v155, v4
	v_and_b32_e32 v153, 0xffff0000, v165
	v_max_f32_e32 v141, v141, v141
	v_max_f32_e32 v148, v148, v148
	v_max_f32_e32 v149, v149, v149
	v_max_f32_e32 v141, v141, v3
	v_max_f32_e32 v148, v148, v3
	v_max_f32_e32 v149, v149, v3
	v_max_f32_e32 v4, v153, v153
	v_pk_mul_f32 v[138:139], v[148:149], v[150:151]
	v_max_f32_e32 v153, v4, v3
	v_pk_mul_f32 v[4:5], v[140:141], v[146:147]
	s_waitcnt vmcnt(0)
	v_lshlrev_b32_e32 v146, 16, v135
	v_and_b32_e32 v147, 0xffff0000, v135
	v_lshlrev_b32_e32 v135, 16, v136
	v_pk_mul_f32 v[20:21], v[20:21], v[138:139]
	v_pk_mul_f32 v[138:139], v[152:153], v[154:155]
	v_max_f32_e32 v135, v135, v135
	v_pk_mul_f32 v[16:17], v[16:17], v[138:139]
	v_pk_mul_f32 v[14:15], v[14:15], v[4:5]
	v_lshlrev_b32_e32 v4, 16, v142
	v_and_b32_e32 v5, 0xffff0000, v142
	v_lshlrev_b32_e32 v138, 16, v144
	v_and_b32_e32 v139, 0xffff0000, v144
	v_lshlrev_b32_e32 v142, 16, v134
	v_and_b32_e32 v144, 0xffff0000, v134
	v_max_f32_e32 v135, 0x1e3ce508, v135
	v_and_b32_e32 v148, 0xffff0000, v136
	v_max_f32_e32 v134, v142, v142
	v_max_f32_e32 v136, v138, v138
	v_rcp_f32_e32 v138, v135
	v_max_f32_e32 v135, v144, v144
	v_max_f32_e32 v134, 0x1e3ce508, v134
	v_max_f32_e32 v135, 0x1e3ce508, v135
	v_lshlrev_b32_e32 v140, 16, v143
	v_and_b32_e32 v141, 0xffff0000, v143
	v_lshlrev_b32_e32 v143, 16, v145
	v_rcp_f32_e32 v134, v134
	v_rcp_f32_e32 v135, v135
	v_lshlrev_b32_e32 v149, 16, v137
	v_max_f32_e32 v143, v143, v143
	v_max_f32_e32 v4, v4, v4
	v_max_f32_e32 v5, v5, v5
	v_max_f32_e32 v144, v143, v3
	v_max_f32_e32 v143, v149, v149
	v_max_f32_e32 v4, v4, v3
	v_max_f32_e32 v5, v5, v3
	v_max_f32_e32 v143, 0x1e3ce508, v143
	v_and_b32_e32 v150, 0xffff0000, v137
	v_max_f32_e32 v142, v146, v146
	v_rcp_f32_e32 v146, v143
	v_max_f32_e32 v143, v147, v147
	v_pk_mul_f32 v[4:5], v[4:5], v[134:135]
	v_max_f32_e32 v137, v139, v139
	v_max_f32_e32 v139, v148, v148
	v_max_f32_e32 v142, 0x1e3ce508, v142
	v_max_f32_e32 v143, 0x1e3ce508, v143
	v_pk_mul_f32 v[10:11], v[10:11], v[4:5]
	v_max_f32_e32 v4, v150, v150
	v_max_f32_e32 v139, 0x1e3ce508, v139
	v_rcp_f32_e32 v142, v142
	v_rcp_f32_e32 v143, v143
	v_max_f32_e32 v4, 0x1e3ce508, v4
	v_rcp_f32_e32 v139, v139
	v_rcp_f32_e32 v147, v4
	v_and_b32_e32 v145, 0xffff0000, v145
	v_max_f32_e32 v140, v140, v140
	v_max_f32_e32 v141, v141, v141
	v_max_f32_e32 v140, v140, v3
	v_max_f32_e32 v141, v141, v3
	v_max_f32_e32 v4, v145, v145
	v_max_f32_e32 v136, v136, v3
	v_max_f32_e32 v137, v137, v3
	v_pk_mul_f32 v[134:135], v[140:141], v[142:143]
	v_max_f32_e32 v145, v4, v3
	v_pk_mul_f32 v[12:13], v[12:13], v[134:135]
	v_pk_mul_f32 v[4:5], v[136:137], v[138:139]
	v_pk_mul_f32 v[134:135], v[144:145], v[146:147]
	v_pk_mul_f32 v[6:7], v[6:7], v[4:5]
	v_pk_mul_f32 v[8:9], v[8:9], v[134:135]
